# k02 + GEMM2 fused-RMSNorm epilogue hand-scheduled: x loads streamed 4 groups deep with in-place add, batched bpermute reductions, SS loads streamed, v_rsq_f32, out stores without nt
# speedup vs baseline: 1.0070x; 1.0038x over previous
.LBB0_670:
	s_waitcnt lgkmcnt(0)
	buffer_inv sc1
	s_waitcnt vmcnt(0)
	global_load_dwordx4 v[212:215], v[136:137], off
	global_load_dwordx4 v[216:219], v[136:137], off offset:64
	global_load_dwordx4 v[220:223], v[136:137], off offset:512
	global_load_dwordx4 v[224:227], v[136:137], off offset:576
	v_lshlrev_b64 v[204:205], 8, v[192:193]
	v_mov_b64_e32 v[206:207], 0x1000
	v_mov_b64_e32 v[208:209], 0x5000
	v_lshl_add_u64 v[204:205], v[132:133], 0, v[204:205]
	global_load_dwordx4 v[144:147], v[204:205], off
	global_load_dwordx4 v[148:151], v[204:205], off offset:64
	global_load_dwordx4 v[152:155], v[204:205], off offset:128
	global_load_dwordx4 v[156:159], v[204:205], off offset:192
	v_lshl_add_u64 v[204:205], v[204:205], 0, v[206:207]
	global_load_dwordx4 v[160:163], v[204:205], off
	global_load_dwordx4 v[164:167], v[204:205], off offset:64
	global_load_dwordx4 v[168:171], v[204:205], off offset:128
	global_load_dwordx4 v[172:175], v[204:205], off offset:192
	v_lshl_add_u64 v[204:205], v[204:205], 0, v[206:207]
	global_load_dwordx4 v[176:179], v[204:205], off
	global_load_dwordx4 v[180:183], v[204:205], off offset:64
	global_load_dwordx4 v[184:187], v[204:205], off offset:128
	global_load_dwordx4 v[188:191], v[204:205], off offset:192
	s_mov_b32 s24, 32
	s_mov_b64 s[22:23], 0
	s_mov_b32 s46, s45
	s_waitcnt vmcnt(8)
	v_add_f32_e32 v144, v144, v145
	v_add_f32_e32 v146, v146, v147
	v_add_f32_e32 v148, v148, v149
	v_add_f32_e32 v150, v150, v151
	v_add_f32_e32 v152, v152, v153
	v_add_f32_e32 v154, v154, v155
	v_add_f32_e32 v156, v156, v157
	v_add_f32_e32 v158, v158, v159
	v_add_f32_e32 v144, v144, v146
	v_add_f32_e32 v148, v148, v150
	v_add_f32_e32 v152, v152, v154
	v_add_f32_e32 v156, v156, v158
	v_add_f32_e32 v144, v144, v148
	v_add_f32_e32 v152, v152, v156
	v_add_f32_e32 v228, v144, v152
	v_lshl_add_u64 v[204:205], v[204:205], 0, v[206:207]
	global_load_dwordx4 v[144:147], v[204:205], off
	global_load_dwordx4 v[148:151], v[204:205], off offset:64
	global_load_dwordx4 v[152:155], v[204:205], off offset:128
	global_load_dwordx4 v[156:159], v[204:205], off offset:192
	s_waitcnt vmcnt(8)
	v_add_f32_e32 v160, v160, v161
	v_add_f32_e32 v162, v162, v163
	v_add_f32_e32 v164, v164, v165
	v_add_f32_e32 v166, v166, v167
	v_add_f32_e32 v168, v168, v169
	v_add_f32_e32 v170, v170, v171
	v_add_f32_e32 v172, v172, v173
	v_add_f32_e32 v174, v174, v175
	v_add_f32_e32 v160, v160, v162
	v_add_f32_e32 v164, v164, v166
	v_add_f32_e32 v168, v168, v170
	v_add_f32_e32 v172, v172, v174
	v_add_f32_e32 v160, v160, v164
	v_add_f32_e32 v168, v168, v172
	v_add_f32_e32 v229, v160, v168
	v_lshl_add_u64 v[204:205], v[204:205], 0, v[208:209]
	global_load_dwordx4 v[160:163], v[204:205], off
	global_load_dwordx4 v[164:167], v[204:205], off offset:64
	global_load_dwordx4 v[168:171], v[204:205], off offset:128
	global_load_dwordx4 v[172:175], v[204:205], off offset:192
	s_waitcnt vmcnt(8)
	v_add_f32_e32 v176, v176, v177
	v_add_f32_e32 v178, v178, v179
	v_add_f32_e32 v180, v180, v181
	v_add_f32_e32 v182, v182, v183
	v_add_f32_e32 v184, v184, v185
	v_add_f32_e32 v186, v186, v187
	v_add_f32_e32 v188, v188, v189
	v_add_f32_e32 v190, v190, v191
	v_add_f32_e32 v176, v176, v178
	v_add_f32_e32 v180, v180, v182
	v_add_f32_e32 v184, v184, v186
	v_add_f32_e32 v188, v188, v190
	v_add_f32_e32 v176, v176, v180
	v_add_f32_e32 v184, v184, v188
	v_add_f32_e32 v230, v176, v184
	v_lshl_add_u64 v[204:205], v[204:205], 0, v[206:207]
	global_load_dwordx4 v[176:179], v[204:205], off
	global_load_dwordx4 v[180:183], v[204:205], off offset:64
	global_load_dwordx4 v[184:187], v[204:205], off offset:128
	global_load_dwordx4 v[188:191], v[204:205], off offset:192
	s_waitcnt vmcnt(8)
	v_add_f32_e32 v144, v144, v145
	v_add_f32_e32 v146, v146, v147
	v_add_f32_e32 v148, v148, v149
	v_add_f32_e32 v150, v150, v151
	v_add_f32_e32 v152, v152, v153
	v_add_f32_e32 v154, v154, v155
	v_add_f32_e32 v156, v156, v157
	v_add_f32_e32 v158, v158, v159
	v_add_f32_e32 v144, v144, v146
	v_add_f32_e32 v148, v148, v150
	v_add_f32_e32 v152, v152, v154
	v_add_f32_e32 v156, v156, v158
	v_add_f32_e32 v144, v144, v148
	v_add_f32_e32 v152, v152, v156
	v_add_f32_e32 v231, v144, v152
	v_lshl_add_u64 v[204:205], v[204:205], 0, v[206:207]
	global_load_dwordx4 v[144:147], v[204:205], off
	global_load_dwordx4 v[148:151], v[204:205], off offset:64
	global_load_dwordx4 v[152:155], v[204:205], off offset:128
	global_load_dwordx4 v[156:159], v[204:205], off offset:192
	s_waitcnt vmcnt(8)
	v_add_f32_e32 v160, v160, v161
	v_add_f32_e32 v162, v162, v163
	v_add_f32_e32 v164, v164, v165
	v_add_f32_e32 v166, v166, v167
	v_add_f32_e32 v168, v168, v169
	v_add_f32_e32 v170, v170, v171
	v_add_f32_e32 v172, v172, v173
	v_add_f32_e32 v174, v174, v175
	v_add_f32_e32 v160, v160, v162
	v_add_f32_e32 v164, v164, v166
	v_add_f32_e32 v168, v168, v170
	v_add_f32_e32 v172, v172, v174
	v_add_f32_e32 v160, v160, v164
	v_add_f32_e32 v168, v168, v172
	v_add_f32_e32 v232, v160, v168
	v_lshl_add_u64 v[204:205], v[204:205], 0, v[206:207]
	global_load_dwordx4 v[160:163], v[204:205], off
	global_load_dwordx4 v[164:167], v[204:205], off offset:64
	global_load_dwordx4 v[168:171], v[204:205], off offset:128
	global_load_dwordx4 v[172:175], v[204:205], off offset:192
	s_waitcnt vmcnt(8)
	v_add_f32_e32 v176, v176, v177
	v_add_f32_e32 v178, v178, v179
	v_add_f32_e32 v180, v180, v181
	v_add_f32_e32 v182, v182, v183
	v_add_f32_e32 v184, v184, v185
	v_add_f32_e32 v186, v186, v187
	v_add_f32_e32 v188, v188, v189
	v_add_f32_e32 v190, v190, v191
	v_add_f32_e32 v176, v176, v178
	v_add_f32_e32 v180, v180, v182
	v_add_f32_e32 v184, v184, v186
	v_add_f32_e32 v188, v188, v190
	v_add_f32_e32 v176, v176, v180
	v_add_f32_e32 v184, v184, v188
	v_add_f32_e32 v233, v176, v184
	s_waitcnt vmcnt(4)
	v_add_f32_e32 v144, v144, v145
	v_add_f32_e32 v146, v146, v147
	v_add_f32_e32 v148, v148, v149
	v_add_f32_e32 v150, v150, v151
	v_add_f32_e32 v152, v152, v153
	v_add_f32_e32 v154, v154, v155
	v_add_f32_e32 v156, v156, v157
	v_add_f32_e32 v158, v158, v159
	v_add_f32_e32 v144, v144, v146
	v_add_f32_e32 v148, v148, v150
	v_add_f32_e32 v152, v152, v154
	v_add_f32_e32 v156, v156, v158
	v_add_f32_e32 v144, v144, v148
	v_add_f32_e32 v152, v152, v156
	v_add_f32_e32 v234, v144, v152
	s_waitcnt vmcnt(0)
	v_add_f32_e32 v160, v160, v161
	v_add_f32_e32 v162, v162, v163
	v_add_f32_e32 v164, v164, v165
	v_add_f32_e32 v166, v166, v167
	v_add_f32_e32 v168, v168, v169
	v_add_f32_e32 v170, v170, v171
	v_add_f32_e32 v172, v172, v173
	v_add_f32_e32 v174, v174, v175
	v_add_f32_e32 v160, v160, v162
	v_add_f32_e32 v164, v164, v166
	v_add_f32_e32 v168, v168, v170
	v_add_f32_e32 v172, v172, v174
	v_add_f32_e32 v160, v160, v164
	v_add_f32_e32 v168, v168, v172
	v_add_f32_e32 v235, v160, v168
	ds_bpermute_b32 v144, v202, v228
	ds_bpermute_b32 v145, v202, v229
	ds_bpermute_b32 v146, v202, v230
	ds_bpermute_b32 v147, v202, v231
	ds_bpermute_b32 v148, v202, v232
	ds_bpermute_b32 v149, v202, v233
	ds_bpermute_b32 v150, v202, v234
	ds_bpermute_b32 v151, v202, v235
	s_waitcnt lgkmcnt(0)
	v_add_f32_e32 v228, v228, v144
	v_add_f32_e32 v229, v229, v145
	v_add_f32_e32 v230, v230, v146
	v_add_f32_e32 v231, v231, v147
	v_add_f32_e32 v232, v232, v148
	v_add_f32_e32 v233, v233, v149
	v_add_f32_e32 v234, v234, v150
	v_add_f32_e32 v235, v235, v151
	ds_bpermute_b32 v144, v203, v228
	ds_bpermute_b32 v145, v203, v229
	ds_bpermute_b32 v146, v203, v230
	ds_bpermute_b32 v147, v203, v231
	ds_bpermute_b32 v148, v203, v232
	ds_bpermute_b32 v149, v203, v233
	ds_bpermute_b32 v150, v203, v234
	ds_bpermute_b32 v151, v203, v235
	s_waitcnt lgkmcnt(0)
	v_add_f32_e32 v228, v228, v144
	v_add_f32_e32 v229, v229, v145
	v_add_f32_e32 v230, v230, v146
	v_add_f32_e32 v231, v231, v147
	v_add_f32_e32 v232, v232, v148
	v_add_f32_e32 v233, v233, v149
	v_add_f32_e32 v234, v234, v150
	v_add_f32_e32 v235, v235, v151
	v_fmamk_f32 v228, v228, 0x39800000, v200
	v_fmamk_f32 v229, v229, 0x39800000, v200
	v_fmamk_f32 v230, v230, 0x39800000, v200
	v_fmamk_f32 v231, v231, 0x39800000, v200
	v_fmamk_f32 v232, v232, 0x39800000, v200
	v_fmamk_f32 v233, v233, 0x39800000, v200
	v_fmamk_f32 v234, v234, 0x39800000, v200
	v_fmamk_f32 v235, v235, 0x39800000, v200
	v_rsq_f32_e32 v228, v228
	v_rsq_f32_e32 v229, v229
	v_rsq_f32_e32 v230, v230
	v_rsq_f32_e32 v231, v231
	v_rsq_f32_e32 v232, v232
	v_rsq_f32_e32 v233, v233
	v_rsq_f32_e32 v234, v234
	v_rsq_f32_e32 v235, v235
	v_lshlrev_b64 v[204:205], 14, v[192:193]
	v_mov_b64_e32 v[206:207], 0x40000
	v_mov_b64_e32 v[208:209], 0x140000
	v_lshl_add_u64 v[204:205], v[138:139], 0, v[204:205]
	v_mul_f32_e32 v124, v228, v124
	v_mul_f32_e32 v125, v228, v125
	v_mul_f32_e32 v126, v228, v126
	v_mul_f32_e32 v127, v228, v127
	v_mul_f32_e32 v120, v228, v120
	v_mul_f32_e32 v121, v228, v121
	v_mul_f32_e32 v122, v228, v122
	v_mul_f32_e32 v123, v228, v123
	v_mul_f32_e32 v116, v228, v116
	v_mul_f32_e32 v117, v228, v117
	v_mul_f32_e32 v118, v228, v118
	v_mul_f32_e32 v119, v228, v119
	v_mul_f32_e32 v112, v228, v112
	v_mul_f32_e32 v113, v228, v113
	v_mul_f32_e32 v114, v228, v114
	v_mul_f32_e32 v115, v228, v115
	v_pk_mul_f32 v[124:125], v[212:213], v[124:125]
	v_pk_mul_f32 v[126:127], v[214:215], v[126:127]
	v_pk_mul_f32 v[120:121], v[216:217], v[120:121]
	v_pk_mul_f32 v[122:123], v[218:219], v[122:123]
	v_pk_mul_f32 v[116:117], v[220:221], v[116:117]
	v_pk_mul_f32 v[118:119], v[222:223], v[118:119]
	v_pk_mul_f32 v[112:113], v[224:225], v[112:113]
	v_pk_mul_f32 v[114:115], v[226:227], v[114:115]
	global_store_dwordx4 v[204:205], v[124:127], off
	global_store_dwordx4 v[204:205], v[120:123], off offset:64
	global_store_dwordx4 v[204:205], v[116:119], off offset:512
	global_store_dwordx4 v[204:205], v[112:115], off offset:576
	v_mul_f32_e32 v108, v229, v108
	v_mul_f32_e32 v109, v229, v109
	v_mul_f32_e32 v110, v229, v110
	v_mul_f32_e32 v111, v229, v111
	v_mul_f32_e32 v104, v229, v104
	v_mul_f32_e32 v105, v229, v105
	v_mul_f32_e32 v106, v229, v106
	v_mul_f32_e32 v107, v229, v107
	v_mul_f32_e32 v100, v229, v100
	v_mul_f32_e32 v101, v229, v101
	v_mul_f32_e32 v102, v229, v102
	v_mul_f32_e32 v103, v229, v103
	v_mul_f32_e32 v96, v229, v96
	v_mul_f32_e32 v97, v229, v97
	v_mul_f32_e32 v98, v229, v98
	v_mul_f32_e32 v99, v229, v99
	v_pk_mul_f32 v[108:109], v[212:213], v[108:109]
	v_pk_mul_f32 v[110:111], v[214:215], v[110:111]
	v_pk_mul_f32 v[104:105], v[216:217], v[104:105]
	v_pk_mul_f32 v[106:107], v[218:219], v[106:107]
	v_pk_mul_f32 v[100:101], v[220:221], v[100:101]
	v_pk_mul_f32 v[102:103], v[222:223], v[102:103]
	v_pk_mul_f32 v[96:97], v[224:225], v[96:97]
	v_pk_mul_f32 v[98:99], v[226:227], v[98:99]
	v_lshl_add_u64 v[204:205], v[204:205], 0, v[206:207]
	global_store_dwordx4 v[204:205], v[108:111], off
	global_store_dwordx4 v[204:205], v[104:107], off offset:64
	global_store_dwordx4 v[204:205], v[100:103], off offset:512
	global_store_dwordx4 v[204:205], v[96:99], off offset:576
	v_mul_f32_e32 v92, v230, v92
	v_mul_f32_e32 v93, v230, v93
	v_mul_f32_e32 v94, v230, v94
	v_mul_f32_e32 v95, v230, v95
	v_mul_f32_e32 v88, v230, v88
	v_mul_f32_e32 v89, v230, v89
	v_mul_f32_e32 v90, v230, v90
	v_mul_f32_e32 v91, v230, v91
	v_mul_f32_e32 v84, v230, v84
	v_mul_f32_e32 v85, v230, v85
	v_mul_f32_e32 v86, v230, v86
	v_mul_f32_e32 v87, v230, v87
	v_mul_f32_e32 v80, v230, v80
	v_mul_f32_e32 v81, v230, v81
	v_mul_f32_e32 v82, v230, v82
	v_mul_f32_e32 v83, v230, v83
	v_pk_mul_f32 v[92:93], v[212:213], v[92:93]
	v_pk_mul_f32 v[94:95], v[214:215], v[94:95]
	v_pk_mul_f32 v[88:89], v[216:217], v[88:89]
	v_pk_mul_f32 v[90:91], v[218:219], v[90:91]
	v_pk_mul_f32 v[84:85], v[220:221], v[84:85]
	v_pk_mul_f32 v[86:87], v[222:223], v[86:87]
	v_pk_mul_f32 v[80:81], v[224:225], v[80:81]
	v_pk_mul_f32 v[82:83], v[226:227], v[82:83]
	v_lshl_add_u64 v[204:205], v[204:205], 0, v[206:207]
	global_store_dwordx4 v[204:205], v[92:95], off
	global_store_dwordx4 v[204:205], v[88:91], off offset:64
	global_store_dwordx4 v[204:205], v[84:87], off offset:512
	global_store_dwordx4 v[204:205], v[80:83], off offset:576
	v_mul_f32_e32 v76, v231, v76
	v_mul_f32_e32 v77, v231, v77
	v_mul_f32_e32 v78, v231, v78
	v_mul_f32_e32 v79, v231, v79
	v_mul_f32_e32 v72, v231, v72
	v_mul_f32_e32 v73, v231, v73
	v_mul_f32_e32 v74, v231, v74
	v_mul_f32_e32 v75, v231, v75
	v_mul_f32_e32 v68, v231, v68
	v_mul_f32_e32 v69, v231, v69
	v_mul_f32_e32 v70, v231, v70
	v_mul_f32_e32 v71, v231, v71
	v_mul_f32_e32 v64, v231, v64
	v_mul_f32_e32 v65, v231, v65
	v_mul_f32_e32 v66, v231, v66
	v_mul_f32_e32 v67, v231, v67
	v_pk_mul_f32 v[76:77], v[212:213], v[76:77]
	v_pk_mul_f32 v[78:79], v[214:215], v[78:79]
	v_pk_mul_f32 v[72:73], v[216:217], v[72:73]
	v_pk_mul_f32 v[74:75], v[218:219], v[74:75]
	v_pk_mul_f32 v[68:69], v[220:221], v[68:69]
	v_pk_mul_f32 v[70:71], v[222:223], v[70:71]
	v_pk_mul_f32 v[64:65], v[224:225], v[64:65]
	v_pk_mul_f32 v[66:67], v[226:227], v[66:67]
	v_lshl_add_u64 v[204:205], v[204:205], 0, v[206:207]
	global_store_dwordx4 v[204:205], v[76:79], off
	global_store_dwordx4 v[204:205], v[72:75], off offset:64
	global_store_dwordx4 v[204:205], v[68:71], off offset:512
	global_store_dwordx4 v[204:205], v[64:67], off offset:576
	v_mul_f32_e32 v60, v232, v60
	v_mul_f32_e32 v61, v232, v61
	v_mul_f32_e32 v62, v232, v62
	v_mul_f32_e32 v63, v232, v63
	v_mul_f32_e32 v56, v232, v56
	v_mul_f32_e32 v57, v232, v57
	v_mul_f32_e32 v58, v232, v58
	v_mul_f32_e32 v59, v232, v59
	v_mul_f32_e32 v52, v232, v52
	v_mul_f32_e32 v53, v232, v53
	v_mul_f32_e32 v54, v232, v54
	v_mul_f32_e32 v55, v232, v55
	v_mul_f32_e32 v48, v232, v48
	v_mul_f32_e32 v49, v232, v49
	v_mul_f32_e32 v50, v232, v50
	v_mul_f32_e32 v51, v232, v51
	v_pk_mul_f32 v[60:61], v[212:213], v[60:61]
	v_pk_mul_f32 v[62:63], v[214:215], v[62:63]
	v_pk_mul_f32 v[56:57], v[216:217], v[56:57]
	v_pk_mul_f32 v[58:59], v[218:219], v[58:59]
	v_pk_mul_f32 v[52:53], v[220:221], v[52:53]
	v_pk_mul_f32 v[54:55], v[222:223], v[54:55]
	v_pk_mul_f32 v[48:49], v[224:225], v[48:49]
	v_pk_mul_f32 v[50:51], v[226:227], v[50:51]
	v_lshl_add_u64 v[204:205], v[204:205], 0, v[208:209]
	global_store_dwordx4 v[204:205], v[60:63], off
	global_store_dwordx4 v[204:205], v[56:59], off offset:64
	global_store_dwordx4 v[204:205], v[52:55], off offset:512
	global_store_dwordx4 v[204:205], v[48:51], off offset:576
	v_mul_f32_e32 v44, v233, v44
	v_mul_f32_e32 v45, v233, v45
	v_mul_f32_e32 v46, v233, v46
	v_mul_f32_e32 v47, v233, v47
	v_mul_f32_e32 v40, v233, v40
	v_mul_f32_e32 v41, v233, v41
	v_mul_f32_e32 v42, v233, v42
	v_mul_f32_e32 v43, v233, v43
	v_mul_f32_e32 v36, v233, v36
	v_mul_f32_e32 v37, v233, v37
	v_mul_f32_e32 v38, v233, v38
	v_mul_f32_e32 v39, v233, v39
	v_mul_f32_e32 v32, v233, v32
	v_mul_f32_e32 v33, v233, v33
	v_mul_f32_e32 v34, v233, v34
	v_mul_f32_e32 v35, v233, v35
	v_pk_mul_f32 v[44:45], v[212:213], v[44:45]
	v_pk_mul_f32 v[46:47], v[214:215], v[46:47]
	v_pk_mul_f32 v[40:41], v[216:217], v[40:41]
	v_pk_mul_f32 v[42:43], v[218:219], v[42:43]
	v_pk_mul_f32 v[36:37], v[220:221], v[36:37]
	v_pk_mul_f32 v[38:39], v[222:223], v[38:39]
	v_pk_mul_f32 v[32:33], v[224:225], v[32:33]
	v_pk_mul_f32 v[34:35], v[226:227], v[34:35]
	v_lshl_add_u64 v[204:205], v[204:205], 0, v[206:207]
	global_store_dwordx4 v[204:205], v[44:47], off
	global_store_dwordx4 v[204:205], v[40:43], off offset:64
	global_store_dwordx4 v[204:205], v[36:39], off offset:512
	global_store_dwordx4 v[204:205], v[32:35], off offset:576
	v_mul_f32_e32 v28, v234, v28
	v_mul_f32_e32 v29, v234, v29
	v_mul_f32_e32 v30, v234, v30
	v_mul_f32_e32 v31, v234, v31
	v_mul_f32_e32 v24, v234, v24
	v_mul_f32_e32 v25, v234, v25
	v_mul_f32_e32 v26, v234, v26
	v_mul_f32_e32 v27, v234, v27
	v_mul_f32_e32 v20, v234, v20
	v_mul_f32_e32 v21, v234, v21
	v_mul_f32_e32 v22, v234, v22
	v_mul_f32_e32 v23, v234, v23
	v_mul_f32_e32 v16, v234, v16
	v_mul_f32_e32 v17, v234, v17
	v_mul_f32_e32 v18, v234, v18
	v_mul_f32_e32 v19, v234, v19
	v_pk_mul_f32 v[28:29], v[212:213], v[28:29]
	v_pk_mul_f32 v[30:31], v[214:215], v[30:31]
	v_pk_mul_f32 v[24:25], v[216:217], v[24:25]
	v_pk_mul_f32 v[26:27], v[218:219], v[26:27]
	v_pk_mul_f32 v[20:21], v[220:221], v[20:21]
	v_pk_mul_f32 v[22:23], v[222:223], v[22:23]
	v_pk_mul_f32 v[16:17], v[224:225], v[16:17]
	v_pk_mul_f32 v[18:19], v[226:227], v[18:19]
	v_lshl_add_u64 v[204:205], v[204:205], 0, v[206:207]
	global_store_dwordx4 v[204:205], v[28:31], off
	global_store_dwordx4 v[204:205], v[24:27], off offset:64
	global_store_dwordx4 v[204:205], v[20:23], off offset:512
	global_store_dwordx4 v[204:205], v[16:19], off offset:576
	v_mul_f32_e32 v12, v235, v12
	v_mul_f32_e32 v13, v235, v13
	v_mul_f32_e32 v14, v235, v14
	v_mul_f32_e32 v15, v235, v15
	v_mul_f32_e32 v8, v235, v8
	v_mul_f32_e32 v9, v235, v9
	v_mul_f32_e32 v10, v235, v10
	v_mul_f32_e32 v11, v235, v11
	v_mul_f32_e32 v4, v235, v4
	v_mul_f32_e32 v5, v235, v5
	v_mul_f32_e32 v6, v235, v6
	v_mul_f32_e32 v7, v235, v7
	v_mul_f32_e32 v0, v235, v0
	v_mul_f32_e32 v1, v235, v1
	v_mul_f32_e32 v2, v235, v2
	v_mul_f32_e32 v3, v235, v3
	v_pk_mul_f32 v[12:13], v[212:213], v[12:13]
	v_pk_mul_f32 v[14:15], v[214:215], v[14:15]
	v_pk_mul_f32 v[8:9], v[216:217], v[8:9]
	v_pk_mul_f32 v[10:11], v[218:219], v[10:11]
	v_pk_mul_f32 v[4:5], v[220:221], v[4:5]
	v_pk_mul_f32 v[6:7], v[222:223], v[6:7]
	v_pk_mul_f32 v[0:1], v[224:225], v[0:1]
	v_pk_mul_f32 v[2:3], v[226:227], v[2:3]
	v_lshl_add_u64 v[204:205], v[204:205], 0, v[206:207]
	global_store_dwordx4 v[204:205], v[12:15], off
	global_store_dwordx4 v[204:205], v[8:11], off offset:64
	global_store_dwordx4 v[204:205], v[4:7], off offset:512
	global_store_dwordx4 v[204:205], v[0:3], off offset:576
	s_and_b64 vcc, exec, s[8:9]
	s_cbranch_vccnz .LBB0_696

.LBB0_672:
	ds_read_b128 v[144:147], v196
	ds_read_b128 v[148:151], v196 offset:1024
	ds_read_b128 v[152:155], v196 offset:2048
	ds_read_b128 v[156:159], v196 offset:3072
	s_add_u32 s4, s0, 0x4000
	s_addc_u32 s5, s1, 0
	s_cmpk_eq_i32 s55, 0x7c
	s_cselect_b32 s26, s48, s4
	s_cselect_b32 s27, s47, s5
	s_cselect_b32 s23, s49, s54
	s_cselect_b32 s22, s52, s53
	s_add_u32 s24, s26, 0x8000
	s_addc_u32 s25, s27, 0
	v_lshl_add_u64 v[192:193], s[0:1], 0, v[140:141]
	s_add_i32 m0, s15, 0xc000
	ds_read_b128 v[160:163], v197
	ds_read_b128 v[164:167], v197 offset:1024
	ds_read_b128 v[168:171], v197 offset:2048
	ds_read_b128 v[172:175], v197 offset:3072
	ds_read_b128 v[176:179], v197 offset:4096
	ds_read_b128 v[180:183], v197 offset:5120
	ds_read_b128 v[184:187], v197 offset:6144
	ds_read_b128 v[188:191], v197 offset:7168
	global_load_lds_dwordx4 v[192:193], off
	v_lshl_add_u64 v[192:193], s[0:1], 0, v[142:143]
	s_add_i32 m0, s15, 0xe000
	s_nop 0
	global_load_lds_dwordx4 v[192:193], off
	s_waitcnt lgkmcnt(8)
	s_barrier
	s_waitcnt lgkmcnt(0)
	s_setprio 1
	s_waitcnt lgkmcnt(0)
	v_mfma_f32_16x16x32_bf16 v[124:127], v[144:147], v[160:163], v[124:127]
	v_mfma_f32_16x16x32_bf16 v[120:123], v[152:155], v[160:163], v[120:123]
	v_mfma_f32_16x16x32_bf16 v[108:111], v[144:147], v[168:171], v[108:111]
	v_mfma_f32_16x16x32_bf16 v[104:107], v[152:155], v[168:171], v[104:107]
	v_mfma_f32_16x16x32_bf16 v[92:95], v[144:147], v[176:179], v[92:95]
	v_mfma_f32_16x16x32_bf16 v[88:91], v[152:155], v[176:179], v[88:91]
	v_mfma_f32_16x16x32_bf16 v[76:79], v[144:147], v[184:187], v[76:79]
	v_mfma_f32_16x16x32_bf16 v[72:75], v[152:155], v[184:187], v[72:75]
	v_mfma_f32_16x16x32_bf16 v[124:127], v[148:151], v[164:167], v[124:127]
	v_mfma_f32_16x16x32_bf16 v[120:123], v[156:159], v[164:167], v[120:123]
	v_mfma_f32_16x16x32_bf16 v[108:111], v[148:151], v[172:175], v[108:111]
	v_mfma_f32_16x16x32_bf16 v[104:107], v[156:159], v[172:175], v[104:107]
	v_mfma_f32_16x16x32_bf16 v[92:95], v[148:151], v[180:183], v[92:95]
	v_mfma_f32_16x16x32_bf16 v[88:91], v[156:159], v[180:183], v[88:91]
	v_mfma_f32_16x16x32_bf16 v[76:79], v[148:151], v[188:191], v[76:79]
	v_mfma_f32_16x16x32_bf16 v[72:75], v[156:159], v[188:191], v[72:75]
	s_setprio 0
	s_barrier
	s_add_i32 s4, s42, s11
	v_lshl_add_u64 v[192:193], s[22:23], 0, v[128:129]
	s_mov_b32 m0, s4
	ds_read_b128 v[202:205], v198
	ds_read_b128 v[206:209], v198 offset:1024
	ds_read_b128 v[212:215], v198 offset:2048
	ds_read_b128 v[216:219], v198 offset:3072
	global_load_lds_dwordx4 v[192:193], off
	v_lshl_add_u64 v[192:193], s[22:23], 0, v[130:131]
	s_add_i32 m0, s4, 0x2000
	s_nop 0
	global_load_lds_dwordx4 v[192:193], off
	s_barrier
	s_waitcnt lgkmcnt(0)
	s_setprio 1
	s_waitcnt lgkmcnt(0)
	v_mfma_f32_16x16x32_bf16 v[116:119], v[202:205], v[160:163], v[116:119]
	v_mfma_f32_16x16x32_bf16 v[112:115], v[212:215], v[160:163], v[112:115]
	v_mfma_f32_16x16x32_bf16 v[100:103], v[202:205], v[168:171], v[100:103]
	v_mfma_f32_16x16x32_bf16 v[96:99], v[212:215], v[168:171], v[96:99]
	v_mfma_f32_16x16x32_bf16 v[84:87], v[202:205], v[176:179], v[84:87]
	v_mfma_f32_16x16x32_bf16 v[80:83], v[212:215], v[176:179], v[80:83]
	v_mfma_f32_16x16x32_bf16 v[68:71], v[202:205], v[184:187], v[68:71]
	v_mfma_f32_16x16x32_bf16 v[64:67], v[212:215], v[184:187], v[64:67]
	v_mfma_f32_16x16x32_bf16 v[116:119], v[206:209], v[164:167], v[116:119]
	v_mfma_f32_16x16x32_bf16 v[112:115], v[216:219], v[164:167], v[112:115]
	v_mfma_f32_16x16x32_bf16 v[100:103], v[206:209], v[172:175], v[100:103]
	v_mfma_f32_16x16x32_bf16 v[96:99], v[216:219], v[172:175], v[96:99]
	v_mfma_f32_16x16x32_bf16 v[84:87], v[206:209], v[180:183], v[84:87]
	v_mfma_f32_16x16x32_bf16 v[80:83], v[216:219], v[180:183], v[80:83]
	v_mfma_f32_16x16x32_bf16 v[68:71], v[206:209], v[188:191], v[68:71]
	v_mfma_f32_16x16x32_bf16 v[64:67], v[216:219], v[188:191], v[64:67]
	s_setprio 0
	s_mov_b32 m0, s15
	v_lshl_add_u64 v[192:193], s[26:27], 0, v[128:129]
	s_barrier
	ds_read_b128 v[160:163], v197 offset:16384
	ds_read_b128 v[164:167], v197 offset:17408
	ds_read_b128 v[168:171], v197 offset:18432
	ds_read_b128 v[172:175], v197 offset:19456
	ds_read_b128 v[176:179], v197 offset:20480
	ds_read_b128 v[180:183], v197 offset:21504
	ds_read_b128 v[184:187], v197 offset:22528
	ds_read_b128 v[188:191], v197 offset:23552
	global_load_lds_dwordx4 v[192:193], off
	v_lshl_add_u64 v[192:193], s[26:27], 0, v[130:131]
	s_mov_b32 m0, s29
	s_nop 0
	global_load_lds_dwordx4 v[192:193], off
	s_barrier
	s_waitcnt lgkmcnt(0)
	s_setprio 1
	s_waitcnt lgkmcnt(0)
	v_mfma_f32_16x16x32_bf16 v[60:63], v[144:147], v[160:163], v[60:63]
	v_mfma_f32_16x16x32_bf16 v[56:59], v[152:155], v[160:163], v[56:59]
	v_mfma_f32_16x16x32_bf16 v[44:47], v[144:147], v[168:171], v[44:47]
	v_mfma_f32_16x16x32_bf16 v[40:43], v[152:155], v[168:171], v[40:43]
	v_mfma_f32_16x16x32_bf16 v[28:31], v[144:147], v[176:179], v[28:31]
	v_mfma_f32_16x16x32_bf16 v[24:27], v[152:155], v[176:179], v[24:27]
	v_mfma_f32_16x16x32_bf16 v[12:15], v[144:147], v[184:187], v[12:15]
	v_mfma_f32_16x16x32_bf16 v[8:11], v[152:155], v[184:187], v[8:11]
	v_mfma_f32_16x16x32_bf16 v[60:63], v[148:151], v[164:167], v[60:63]
	v_mfma_f32_16x16x32_bf16 v[56:59], v[156:159], v[164:167], v[56:59]
	v_mfma_f32_16x16x32_bf16 v[44:47], v[148:151], v[172:175], v[44:47]
	v_mfma_f32_16x16x32_bf16 v[40:43], v[156:159], v[172:175], v[40:43]
	v_mfma_f32_16x16x32_bf16 v[28:31], v[148:151], v[180:183], v[28:31]
	v_mfma_f32_16x16x32_bf16 v[24:27], v[156:159], v[180:183], v[24:27]
	v_mfma_f32_16x16x32_bf16 v[12:15], v[148:151], v[188:191], v[12:15]
	v_mfma_f32_16x16x32_bf16 v[8:11], v[156:159], v[188:191], v[8:11]
	s_setprio 0
	s_barrier
	s_add_u32 s56, s22, 0x4000
	s_addc_u32 s57, s23, 0
	s_add_i32 s4, s43, s11
	v_lshl_add_u64 v[144:145], s[56:57], 0, v[128:129]
	s_mov_b32 m0, s4
	s_nop 0
	global_load_lds_dwordx4 v[144:145], off
	v_lshl_add_u64 v[144:145], s[56:57], 0, v[130:131]
	s_add_i32 m0, s4, 0x2000
	s_nop 0
	global_load_lds_dwordx4 v[144:145], off
	s_waitcnt vmcnt(6)
	s_barrier
	s_setprio 1
	v_mfma_f32_16x16x32_bf16 v[52:55], v[202:205], v[160:163], v[52:55]
	v_mfma_f32_16x16x32_bf16 v[48:51], v[212:215], v[160:163], v[48:51]
	v_mfma_f32_16x16x32_bf16 v[36:39], v[202:205], v[168:171], v[36:39]
	v_mfma_f32_16x16x32_bf16 v[32:35], v[212:215], v[168:171], v[32:35]
	v_mfma_f32_16x16x32_bf16 v[20:23], v[202:205], v[176:179], v[20:23]
	v_mfma_f32_16x16x32_bf16 v[16:19], v[212:215], v[176:179], v[16:19]
	v_mfma_f32_16x16x32_bf16 v[4:7], v[202:205], v[184:187], v[4:7]
	v_mfma_f32_16x16x32_bf16 v[0:3], v[212:215], v[184:187], v[0:3]
	v_mfma_f32_16x16x32_bf16 v[52:55], v[206:209], v[164:167], v[52:55]
	v_mfma_f32_16x16x32_bf16 v[48:51], v[216:219], v[164:167], v[48:51]
	v_mfma_f32_16x16x32_bf16 v[36:39], v[206:209], v[172:175], v[36:39]
	v_mfma_f32_16x16x32_bf16 v[32:35], v[216:219], v[172:175], v[32:35]
	v_mfma_f32_16x16x32_bf16 v[20:23], v[206:209], v[180:183], v[20:23]
	v_mfma_f32_16x16x32_bf16 v[16:19], v[216:219], v[180:183], v[16:19]
	v_mfma_f32_16x16x32_bf16 v[4:7], v[206:209], v[188:191], v[4:7]
	v_mfma_f32_16x16x32_bf16 v[0:3], v[216:219], v[188:191], v[0:3]
	s_setprio 0
	s_add_i32 s4, 0, 0x18000
	v_add_u32_e32 v156, s4, v195
	s_barrier
	ds_read_b128 v[144:147], v156
	ds_read_b128 v[148:151], v156 offset:1024
	ds_read_b128 v[152:155], v156 offset:2048
	ds_read_b128 v[156:159], v156 offset:3072
	s_add_u32 s26, s26, 0x4000
	s_addc_u32 s27, s27, 0
	s_mov_b32 m0, s30
	v_lshl_add_u64 v[192:193], s[26:27], 0, v[128:129]
	ds_read_b128 v[160:163], v197 offset:32768
	ds_read_b128 v[164:167], v197 offset:33792
	ds_read_b128 v[168:171], v197 offset:34816
	ds_read_b128 v[172:175], v197 offset:35840
	ds_read_b128 v[176:179], v197 offset:36864
	ds_read_b128 v[180:183], v197 offset:37888
	ds_read_b128 v[184:187], v197 offset:38912
	ds_read_b128 v[188:191], v197 offset:39936
	global_load_lds_dwordx4 v[192:193], off
	v_lshl_add_u64 v[192:193], s[26:27], 0, v[130:131]
	s_mov_b32 m0, s31
	s_nop 0
	global_load_lds_dwordx4 v[192:193], off
	s_waitcnt lgkmcnt(8)
	s_barrier
	s_waitcnt lgkmcnt(0)
	s_setprio 1
	s_waitcnt lgkmcnt(0)
	v_mfma_f32_16x16x32_bf16 v[124:127], v[144:147], v[160:163], v[124:127]
	v_mfma_f32_16x16x32_bf16 v[120:123], v[152:155], v[160:163], v[120:123]
	v_mfma_f32_16x16x32_bf16 v[108:111], v[144:147], v[168:171], v[108:111]
	v_mfma_f32_16x16x32_bf16 v[104:107], v[152:155], v[168:171], v[104:107]
	v_mfma_f32_16x16x32_bf16 v[92:95], v[144:147], v[176:179], v[92:95]
	v_mfma_f32_16x16x32_bf16 v[88:91], v[152:155], v[176:179], v[88:91]
	v_mfma_f32_16x16x32_bf16 v[76:79], v[144:147], v[184:187], v[76:79]
	v_mfma_f32_16x16x32_bf16 v[72:75], v[152:155], v[184:187], v[72:75]
	v_mfma_f32_16x16x32_bf16 v[124:127], v[148:151], v[164:167], v[124:127]
	v_mfma_f32_16x16x32_bf16 v[120:123], v[156:159], v[164:167], v[120:123]
	v_mfma_f32_16x16x32_bf16 v[108:111], v[148:151], v[172:175], v[108:111]
	v_mfma_f32_16x16x32_bf16 v[104:107], v[156:159], v[172:175], v[104:107]
	v_mfma_f32_16x16x32_bf16 v[92:95], v[148:151], v[180:183], v[92:95]
	v_mfma_f32_16x16x32_bf16 v[88:91], v[156:159], v[180:183], v[88:91]
	v_mfma_f32_16x16x32_bf16 v[76:79], v[148:151], v[188:191], v[76:79]
	v_mfma_f32_16x16x32_bf16 v[72:75], v[156:159], v[188:191], v[72:75]
	s_setprio 0
	s_barrier
	s_add_i32 s5, 0, 0x1c000
	s_add_u32 s26, s22, 0x8000
	v_add_u32_e32 v192, s5, v195
	s_addc_u32 s27, s23, 0
	s_add_i32 s4, s4, s11
	ds_read_b128 v[202:205], v192
	ds_read_b128 v[206:209], v192 offset:1024
	ds_read_b128 v[212:215], v192 offset:2048
	ds_read_b128 v[216:219], v192 offset:3072
	v_lshl_add_u64 v[192:193], s[26:27], 0, v[128:129]
	s_mov_b32 m0, s4
	s_nop 0
	global_load_lds_dwordx4 v[192:193], off
	v_lshl_add_u64 v[192:193], s[26:27], 0, v[130:131]
	s_add_i32 m0, s4, 0x2000
	s_nop 0
	global_load_lds_dwordx4 v[192:193], off
	s_barrier
	s_waitcnt lgkmcnt(0)
	s_setprio 1
	s_waitcnt lgkmcnt(0)
	v_mfma_f32_16x16x32_bf16 v[116:119], v[202:205], v[160:163], v[116:119]
	v_mfma_f32_16x16x32_bf16 v[112:115], v[212:215], v[160:163], v[112:115]
	v_mfma_f32_16x16x32_bf16 v[100:103], v[202:205], v[168:171], v[100:103]
	v_mfma_f32_16x16x32_bf16 v[96:99], v[212:215], v[168:171], v[96:99]
	v_mfma_f32_16x16x32_bf16 v[84:87], v[202:205], v[176:179], v[84:87]
	v_mfma_f32_16x16x32_bf16 v[80:83], v[212:215], v[176:179], v[80:83]
	v_mfma_f32_16x16x32_bf16 v[68:71], v[202:205], v[184:187], v[68:71]
	v_mfma_f32_16x16x32_bf16 v[64:67], v[212:215], v[184:187], v[64:67]
	v_mfma_f32_16x16x32_bf16 v[116:119], v[206:209], v[164:167], v[116:119]
	v_mfma_f32_16x16x32_bf16 v[112:115], v[216:219], v[164:167], v[112:115]
	v_mfma_f32_16x16x32_bf16 v[100:103], v[206:209], v[172:175], v[100:103]
	v_mfma_f32_16x16x32_bf16 v[96:99], v[216:219], v[172:175], v[96:99]
	v_mfma_f32_16x16x32_bf16 v[84:87], v[206:209], v[180:183], v[84:87]
	v_mfma_f32_16x16x32_bf16 v[80:83], v[216:219], v[180:183], v[80:83]
	v_mfma_f32_16x16x32_bf16 v[68:71], v[206:209], v[188:191], v[68:71]
	v_mfma_f32_16x16x32_bf16 v[64:67], v[216:219], v[188:191], v[64:67]
	s_setprio 0
	s_mov_b32 m0, s40
	v_lshl_add_u64 v[192:193], s[24:25], 0, v[128:129]
	s_barrier
	ds_read_b128 v[160:163], v197 offset:49152
	ds_read_b128 v[164:167], v197 offset:50176
	ds_read_b128 v[168:171], v197 offset:51200
	ds_read_b128 v[172:175], v197 offset:52224
	ds_read_b128 v[176:179], v197 offset:53248
	ds_read_b128 v[180:183], v197 offset:54272
	ds_read_b128 v[184:187], v197 offset:55296
	ds_read_b128 v[188:191], v197 offset:56320
	global_load_lds_dwordx4 v[192:193], off
	v_lshl_add_u64 v[192:193], s[24:25], 0, v[130:131]
	s_mov_b32 m0, s41
	s_nop 0
	global_load_lds_dwordx4 v[192:193], off
	s_barrier
	s_waitcnt lgkmcnt(0)
	s_setprio 1
	s_waitcnt lgkmcnt(0)
	v_mfma_f32_16x16x32_bf16 v[60:63], v[144:147], v[160:163], v[60:63]
	v_mfma_f32_16x16x32_bf16 v[56:59], v[152:155], v[160:163], v[56:59]
	v_mfma_f32_16x16x32_bf16 v[44:47], v[144:147], v[168:171], v[44:47]
	v_mfma_f32_16x16x32_bf16 v[40:43], v[152:155], v[168:171], v[40:43]
	v_mfma_f32_16x16x32_bf16 v[28:31], v[144:147], v[176:179], v[28:31]
	v_mfma_f32_16x16x32_bf16 v[24:27], v[152:155], v[176:179], v[24:27]
	v_mfma_f32_16x16x32_bf16 v[12:15], v[144:147], v[184:187], v[12:15]
	v_mfma_f32_16x16x32_bf16 v[8:11], v[152:155], v[184:187], v[8:11]
	v_mfma_f32_16x16x32_bf16 v[60:63], v[148:151], v[164:167], v[60:63]
	v_mfma_f32_16x16x32_bf16 v[56:59], v[156:159], v[164:167], v[56:59]
	v_mfma_f32_16x16x32_bf16 v[44:47], v[148:151], v[172:175], v[44:47]
	v_mfma_f32_16x16x32_bf16 v[40:43], v[156:159], v[172:175], v[40:43]
	v_mfma_f32_16x16x32_bf16 v[28:31], v[148:151], v[180:183], v[28:31]
	v_mfma_f32_16x16x32_bf16 v[24:27], v[156:159], v[180:183], v[24:27]
	v_mfma_f32_16x16x32_bf16 v[12:15], v[148:151], v[188:191], v[12:15]
	v_mfma_f32_16x16x32_bf16 v[8:11], v[156:159], v[188:191], v[8:11]
	s_setprio 0
	s_barrier
	s_add_u32 s22, s22, 0xc000
	s_addc_u32 s23, s23, 0
	s_add_i32 s4, s5, s11
	v_lshl_add_u64 v[144:145], s[22:23], 0, v[128:129]
	s_mov_b32 m0, s4
	s_nop 0
	global_load_lds_dwordx4 v[144:145], off
	v_lshl_add_u64 v[144:145], s[22:23], 0, v[130:131]
	s_add_i32 m0, s4, 0x2000
	s_nop 0
	global_load_lds_dwordx4 v[144:145], off
	s_waitcnt vmcnt(6)
	s_barrier
	s_setprio 1
	v_mfma_f32_16x16x32_bf16 v[52:55], v[202:205], v[160:163], v[52:55]
	v_mfma_f32_16x16x32_bf16 v[48:51], v[212:215], v[160:163], v[48:51]
	v_mfma_f32_16x16x32_bf16 v[36:39], v[202:205], v[168:171], v[36:39]
	v_mfma_f32_16x16x32_bf16 v[32:35], v[212:215], v[168:171], v[32:35]
	v_mfma_f32_16x16x32_bf16 v[20:23], v[202:205], v[176:179], v[20:23]
	v_mfma_f32_16x16x32_bf16 v[16:19], v[212:215], v[176:179], v[16:19]
	v_mfma_f32_16x16x32_bf16 v[4:7], v[202:205], v[184:187], v[4:7]
	v_mfma_f32_16x16x32_bf16 v[0:3], v[212:215], v[184:187], v[0:3]
	v_mfma_f32_16x16x32_bf16 v[52:55], v[206:209], v[164:167], v[52:55]
	v_mfma_f32_16x16x32_bf16 v[48:51], v[216:219], v[164:167], v[48:51]
	v_mfma_f32_16x16x32_bf16 v[36:39], v[206:209], v[172:175], v[36:39]
	v_mfma_f32_16x16x32_bf16 v[32:35], v[216:219], v[172:175], v[32:35]
	v_mfma_f32_16x16x32_bf16 v[20:23], v[206:209], v[180:183], v[20:23]
	v_mfma_f32_16x16x32_bf16 v[16:19], v[216:219], v[180:183], v[16:19]
	v_mfma_f32_16x16x32_bf16 v[4:7], v[206:209], v[188:191], v[4:7]
	v_mfma_f32_16x16x32_bf16 v[0:3], v[216:219], v[188:191], v[0:3]
	s_setprio 0
	s_add_i32 s55, s55, 2
	s_add_u32 s0, s0, 0x10000
	s_addc_u32 s1, s1, 0
	s_add_u32 s53, s53, 0x10000
	s_addc_u32 s54, s54, 0
	s_cmpk_gt_u32 s55, 0x7d
	s_barrier
	s_cbranch_scc0 .LBB0_672
	v_lshl_add_u32 v192, s46, 8, v194
	v_mov_b32_e32 v193, 0
	v_mov_b64_e32 v[206:207], 0x40000
	v_mov_b64_e32 v[208:209], 0x140000
	v_lshlrev_b64 v[204:205], 14, v[192:193]
	v_xor_b32_e32 v202, 16, v199
	v_lshl_add_u64 v[204:205], v[134:135], 0, v[204:205]
	global_load_dwordx4 v[144:147], v[204:205], off nt
	global_load_dwordx4 v[148:151], v[204:205], off offset:64 nt
	global_load_dwordx4 v[152:155], v[204:205], off offset:512 nt
	global_load_dwordx4 v[156:159], v[204:205], off offset:576 nt
	v_lshl_add_u64 v[204:205], v[204:205], 0, v[206:207]
	global_load_dwordx4 v[160:163], v[204:205], off nt
	global_load_dwordx4 v[164:167], v[204:205], off offset:64 nt
	global_load_dwordx4 v[168:171], v[204:205], off offset:512 nt
	global_load_dwordx4 v[172:175], v[204:205], off offset:576 nt
	v_lshl_add_u64 v[204:205], v[204:205], 0, v[206:207]
	global_load_dwordx4 v[176:179], v[204:205], off nt
	global_load_dwordx4 v[180:183], v[204:205], off offset:64 nt
	global_load_dwordx4 v[184:187], v[204:205], off offset:512 nt
	global_load_dwordx4 v[188:191], v[204:205], off offset:576 nt
	v_lshl_add_u64 v[204:205], v[204:205], 0, v[206:207]
	global_load_dwordx4 v[212:215], v[204:205], off nt
	global_load_dwordx4 v[216:219], v[204:205], off offset:64 nt
	global_load_dwordx4 v[220:223], v[204:205], off offset:512 nt
	global_load_dwordx4 v[224:227], v[204:205], off offset:576 nt
	v_xor_b32_e32 v203, 32, v199
	v_lshlrev_b32_e32 v202, 2, v202
	v_lshlrev_b32_e32 v203, 2, v203
	s_waitcnt vmcnt(12)
	v_pk_add_f32 v[124:125], v[124:125], v[144:145]
	v_pk_add_f32 v[126:127], v[126:127], v[146:147]
	v_pk_add_f32 v[120:121], v[120:121], v[148:149]
	v_pk_add_f32 v[122:123], v[122:123], v[150:151]
	v_pk_add_f32 v[116:117], v[116:117], v[152:153]
	v_pk_add_f32 v[118:119], v[118:119], v[154:155]
	v_pk_add_f32 v[112:113], v[112:113], v[156:157]
	v_pk_add_f32 v[114:115], v[114:115], v[158:159]
	v_lshl_add_u64 v[204:205], v[204:205], 0, v[208:209]
	global_load_dwordx4 v[144:147], v[204:205], off nt
	global_load_dwordx4 v[148:151], v[204:205], off offset:64 nt
	global_load_dwordx4 v[152:155], v[204:205], off offset:512 nt
	global_load_dwordx4 v[156:159], v[204:205], off offset:576 nt
	v_mul_f32_e32 v236, v125, v125
	v_mul_f32_e32 v237, v121, v121
	v_mul_f32_e32 v238, v117, v117
	v_mul_f32_e32 v239, v113, v113
	v_fmac_f32_e32 v236, v124, v124
	v_fmac_f32_e32 v237, v120, v120
	v_fmac_f32_e32 v238, v116, v116
	v_fmac_f32_e32 v239, v112, v112
	v_fmac_f32_e32 v236, v126, v126
	v_fmac_f32_e32 v237, v122, v122
	v_fmac_f32_e32 v238, v118, v118
	v_fmac_f32_e32 v239, v114, v114
	v_fmac_f32_e32 v236, v127, v127
	v_fmac_f32_e32 v237, v123, v123
	v_fmac_f32_e32 v238, v119, v119
	v_fmac_f32_e32 v239, v115, v115
	v_add_f32_e32 v236, v236, v237
	v_add_f32_e32 v238, v238, v239
	v_add_f32_e32 v228, v236, v238
	s_waitcnt vmcnt(12)
	v_pk_add_f32 v[108:109], v[108:109], v[160:161]
	v_pk_add_f32 v[110:111], v[110:111], v[162:163]
	v_pk_add_f32 v[104:105], v[104:105], v[164:165]
	v_pk_add_f32 v[106:107], v[106:107], v[166:167]
	v_pk_add_f32 v[100:101], v[100:101], v[168:169]
	v_pk_add_f32 v[102:103], v[102:103], v[170:171]
	v_pk_add_f32 v[96:97], v[96:97], v[172:173]
	v_pk_add_f32 v[98:99], v[98:99], v[174:175]
	v_lshl_add_u64 v[204:205], v[204:205], 0, v[206:207]
	global_load_dwordx4 v[160:163], v[204:205], off nt
	global_load_dwordx4 v[164:167], v[204:205], off offset:64 nt
	global_load_dwordx4 v[168:171], v[204:205], off offset:512 nt
	global_load_dwordx4 v[172:175], v[204:205], off offset:576 nt
	v_mul_f32_e32 v236, v109, v109
	v_mul_f32_e32 v237, v105, v105
	v_mul_f32_e32 v238, v101, v101
	v_mul_f32_e32 v239, v97, v97
	v_fmac_f32_e32 v236, v108, v108
	v_fmac_f32_e32 v237, v104, v104
	v_fmac_f32_e32 v238, v100, v100
	v_fmac_f32_e32 v239, v96, v96
	v_fmac_f32_e32 v236, v110, v110
	v_fmac_f32_e32 v237, v106, v106
	v_fmac_f32_e32 v238, v102, v102
	v_fmac_f32_e32 v239, v98, v98
	v_fmac_f32_e32 v236, v111, v111
	v_fmac_f32_e32 v237, v107, v107
	v_fmac_f32_e32 v238, v103, v103
	v_fmac_f32_e32 v239, v99, v99
	v_add_f32_e32 v236, v236, v237
	v_add_f32_e32 v238, v238, v239
	v_add_f32_e32 v229, v236, v238
	s_waitcnt vmcnt(12)
	v_pk_add_f32 v[92:93], v[92:93], v[176:177]
	v_pk_add_f32 v[94:95], v[94:95], v[178:179]
	v_pk_add_f32 v[88:89], v[88:89], v[180:181]
	v_pk_add_f32 v[90:91], v[90:91], v[182:183]
	v_pk_add_f32 v[84:85], v[84:85], v[184:185]
	v_pk_add_f32 v[86:87], v[86:87], v[186:187]
	v_pk_add_f32 v[80:81], v[80:81], v[188:189]
	v_pk_add_f32 v[82:83], v[82:83], v[190:191]
	v_lshl_add_u64 v[204:205], v[204:205], 0, v[206:207]
	global_load_dwordx4 v[176:179], v[204:205], off nt
	global_load_dwordx4 v[180:183], v[204:205], off offset:64 nt
	global_load_dwordx4 v[184:187], v[204:205], off offset:512 nt
	global_load_dwordx4 v[188:191], v[204:205], off offset:576 nt
	v_mul_f32_e32 v236, v93, v93
	v_mul_f32_e32 v237, v89, v89
	v_mul_f32_e32 v238, v85, v85
	v_mul_f32_e32 v239, v81, v81
	v_fmac_f32_e32 v236, v92, v92
	v_fmac_f32_e32 v237, v88, v88
	v_fmac_f32_e32 v238, v84, v84
	v_fmac_f32_e32 v239, v80, v80
	v_fmac_f32_e32 v236, v94, v94
	v_fmac_f32_e32 v237, v90, v90
	v_fmac_f32_e32 v238, v86, v86
	v_fmac_f32_e32 v239, v82, v82
	v_fmac_f32_e32 v236, v95, v95
	v_fmac_f32_e32 v237, v91, v91
	v_fmac_f32_e32 v238, v87, v87
	v_fmac_f32_e32 v239, v83, v83
	v_add_f32_e32 v236, v236, v237
	v_add_f32_e32 v238, v238, v239
	v_add_f32_e32 v230, v236, v238
	s_waitcnt vmcnt(12)
	v_pk_add_f32 v[76:77], v[76:77], v[212:213]
	v_pk_add_f32 v[78:79], v[78:79], v[214:215]
	v_pk_add_f32 v[72:73], v[72:73], v[216:217]
	v_pk_add_f32 v[74:75], v[74:75], v[218:219]
	v_pk_add_f32 v[68:69], v[68:69], v[220:221]
	v_pk_add_f32 v[70:71], v[70:71], v[222:223]
	v_pk_add_f32 v[64:65], v[64:65], v[224:225]
	v_pk_add_f32 v[66:67], v[66:67], v[226:227]
	v_lshl_add_u64 v[204:205], v[204:205], 0, v[206:207]
	global_load_dwordx4 v[212:215], v[204:205], off nt
	global_load_dwordx4 v[216:219], v[204:205], off offset:64 nt
	global_load_dwordx4 v[220:223], v[204:205], off offset:512 nt
	global_load_dwordx4 v[224:227], v[204:205], off offset:576 nt
	v_mul_f32_e32 v236, v77, v77
	v_mul_f32_e32 v237, v73, v73
	v_mul_f32_e32 v238, v69, v69
	v_mul_f32_e32 v239, v65, v65
	v_fmac_f32_e32 v236, v76, v76
	v_fmac_f32_e32 v237, v72, v72
	v_fmac_f32_e32 v238, v68, v68
	v_fmac_f32_e32 v239, v64, v64
	v_fmac_f32_e32 v236, v78, v78
	v_fmac_f32_e32 v237, v74, v74
	v_fmac_f32_e32 v238, v70, v70
	v_fmac_f32_e32 v239, v66, v66
	v_fmac_f32_e32 v236, v79, v79
	v_fmac_f32_e32 v237, v75, v75
	v_fmac_f32_e32 v238, v71, v71
	v_fmac_f32_e32 v239, v67, v67
	v_add_f32_e32 v236, v236, v237
	v_add_f32_e32 v238, v238, v239
	v_add_f32_e32 v231, v236, v238
	s_waitcnt vmcnt(12)
	v_pk_add_f32 v[60:61], v[60:61], v[144:145]
	v_pk_add_f32 v[62:63], v[62:63], v[146:147]
	v_pk_add_f32 v[56:57], v[56:57], v[148:149]
	v_pk_add_f32 v[58:59], v[58:59], v[150:151]
	v_pk_add_f32 v[52:53], v[52:53], v[152:153]
	v_pk_add_f32 v[54:55], v[54:55], v[154:155]
	v_pk_add_f32 v[48:49], v[48:49], v[156:157]
	v_pk_add_f32 v[50:51], v[50:51], v[158:159]
	v_mul_f32_e32 v236, v61, v61
	v_mul_f32_e32 v237, v57, v57
	v_mul_f32_e32 v238, v53, v53
	v_mul_f32_e32 v239, v49, v49
	v_fmac_f32_e32 v236, v60, v60
	v_fmac_f32_e32 v237, v56, v56
	v_fmac_f32_e32 v238, v52, v52
	v_fmac_f32_e32 v239, v48, v48
	v_fmac_f32_e32 v236, v62, v62
	v_fmac_f32_e32 v237, v58, v58
	v_fmac_f32_e32 v238, v54, v54
	v_fmac_f32_e32 v239, v50, v50
	v_fmac_f32_e32 v236, v63, v63
	v_fmac_f32_e32 v237, v59, v59
	v_fmac_f32_e32 v238, v55, v55
	v_fmac_f32_e32 v239, v51, v51
	v_add_f32_e32 v236, v236, v237
	v_add_f32_e32 v238, v238, v239
	v_add_f32_e32 v232, v236, v238
	s_waitcnt vmcnt(8)
	v_pk_add_f32 v[44:45], v[44:45], v[160:161]
	v_pk_add_f32 v[46:47], v[46:47], v[162:163]
	v_pk_add_f32 v[40:41], v[40:41], v[164:165]
	v_pk_add_f32 v[42:43], v[42:43], v[166:167]
	v_pk_add_f32 v[36:37], v[36:37], v[168:169]
	v_pk_add_f32 v[38:39], v[38:39], v[170:171]
	v_pk_add_f32 v[32:33], v[32:33], v[172:173]
	v_pk_add_f32 v[34:35], v[34:35], v[174:175]
	v_mul_f32_e32 v236, v45, v45
	v_mul_f32_e32 v237, v41, v41
	v_mul_f32_e32 v238, v37, v37
	v_mul_f32_e32 v239, v33, v33
	v_fmac_f32_e32 v236, v44, v44
	v_fmac_f32_e32 v237, v40, v40
	v_fmac_f32_e32 v238, v36, v36
	v_fmac_f32_e32 v239, v32, v32
	v_fmac_f32_e32 v236, v46, v46
	v_fmac_f32_e32 v237, v42, v42
	v_fmac_f32_e32 v238, v38, v38
	v_fmac_f32_e32 v239, v34, v34
	v_fmac_f32_e32 v236, v47, v47
	v_fmac_f32_e32 v237, v43, v43
	v_fmac_f32_e32 v238, v39, v39
	v_fmac_f32_e32 v239, v35, v35
	v_add_f32_e32 v236, v236, v237
	v_add_f32_e32 v238, v238, v239
	v_add_f32_e32 v233, v236, v238
	s_waitcnt vmcnt(4)
	v_pk_add_f32 v[28:29], v[28:29], v[176:177]
	v_pk_add_f32 v[30:31], v[30:31], v[178:179]
	v_pk_add_f32 v[24:25], v[24:25], v[180:181]
	v_pk_add_f32 v[26:27], v[26:27], v[182:183]
	v_pk_add_f32 v[20:21], v[20:21], v[184:185]
	v_pk_add_f32 v[22:23], v[22:23], v[186:187]
	v_pk_add_f32 v[16:17], v[16:17], v[188:189]
	v_pk_add_f32 v[18:19], v[18:19], v[190:191]
	v_mul_f32_e32 v236, v29, v29
	v_mul_f32_e32 v237, v25, v25
	v_mul_f32_e32 v238, v21, v21
	v_mul_f32_e32 v239, v17, v17
	v_fmac_f32_e32 v236, v28, v28
	v_fmac_f32_e32 v237, v24, v24
	v_fmac_f32_e32 v238, v20, v20
	v_fmac_f32_e32 v239, v16, v16
	v_fmac_f32_e32 v236, v30, v30
	v_fmac_f32_e32 v237, v26, v26
	v_fmac_f32_e32 v238, v22, v22
	v_fmac_f32_e32 v239, v18, v18
	v_fmac_f32_e32 v236, v31, v31
	v_fmac_f32_e32 v237, v27, v27
	v_fmac_f32_e32 v238, v23, v23
	v_fmac_f32_e32 v239, v19, v19
	v_add_f32_e32 v236, v236, v237
	v_add_f32_e32 v238, v238, v239
	v_add_f32_e32 v234, v236, v238
	s_waitcnt vmcnt(0)
	v_pk_add_f32 v[12:13], v[12:13], v[212:213]
	v_pk_add_f32 v[14:15], v[14:15], v[214:215]
	v_pk_add_f32 v[8:9], v[8:9], v[216:217]
	v_pk_add_f32 v[10:11], v[10:11], v[218:219]
	v_pk_add_f32 v[4:5], v[4:5], v[220:221]
	v_pk_add_f32 v[6:7], v[6:7], v[222:223]
	v_pk_add_f32 v[0:1], v[0:1], v[224:225]
	v_pk_add_f32 v[2:3], v[2:3], v[226:227]
	v_mul_f32_e32 v236, v13, v13
	v_mul_f32_e32 v237, v9, v9
	v_mul_f32_e32 v238, v5, v5
	v_mul_f32_e32 v239, v1, v1
	v_fmac_f32_e32 v236, v12, v12
	v_fmac_f32_e32 v237, v8, v8
	v_fmac_f32_e32 v238, v4, v4
	v_fmac_f32_e32 v239, v0, v0
	v_fmac_f32_e32 v236, v14, v14
	v_fmac_f32_e32 v237, v10, v10
	v_fmac_f32_e32 v238, v6, v6
	v_fmac_f32_e32 v239, v2, v2
	v_fmac_f32_e32 v236, v15, v15
	v_fmac_f32_e32 v237, v11, v11
	v_fmac_f32_e32 v238, v7, v7
	v_fmac_f32_e32 v239, v3, v3
	v_add_f32_e32 v236, v236, v237
	v_add_f32_e32 v238, v238, v239
	v_add_f32_e32 v235, v236, v238
	ds_bpermute_b32 v144, v202, v228
	ds_bpermute_b32 v145, v202, v229
	ds_bpermute_b32 v146, v202, v230
	ds_bpermute_b32 v147, v202, v231
	ds_bpermute_b32 v148, v202, v232
	ds_bpermute_b32 v149, v202, v233
	ds_bpermute_b32 v150, v202, v234
	ds_bpermute_b32 v151, v202, v235
	s_waitcnt lgkmcnt(0)
	v_add_f32_e32 v228, v228, v144
	v_add_f32_e32 v229, v229, v145
	v_add_f32_e32 v230, v230, v146
	v_add_f32_e32 v231, v231, v147
	v_add_f32_e32 v232, v232, v148
	v_add_f32_e32 v233, v233, v149
	v_add_f32_e32 v234, v234, v150
	v_add_f32_e32 v235, v235, v151
	ds_bpermute_b32 v144, v203, v228
	ds_bpermute_b32 v145, v203, v229
	ds_bpermute_b32 v146, v203, v230
	ds_bpermute_b32 v147, v203, v231
	ds_bpermute_b32 v148, v203, v232
	ds_bpermute_b32 v149, v203, v233
	ds_bpermute_b32 v150, v203, v234
	ds_bpermute_b32 v151, v203, v235
	s_waitcnt lgkmcnt(0)
	v_add_f32_e32 v228, v228, v144
	v_add_f32_e32 v229, v229, v145
	v_add_f32_e32 v230, v230, v146
	v_add_f32_e32 v231, v231, v147
	v_add_f32_e32 v232, v232, v148
	v_add_f32_e32 v233, v233, v149
	v_add_f32_e32 v234, v234, v150
	v_add_f32_e32 v235, v235, v151
	v_lshlrev_b64 v[204:205], 8, v[192:193]
	v_mov_b64_e32 v[206:207], 0x1000
	v_mov_b64_e32 v[208:209], 0x5000
	v_lshl_add_u64 v[204:205], s[20:21], 0, v[204:205]
	s_and_saveexec_b64 s[0:1], s[2:3]
	global_store_dword v[204:205], v228, off sc1
	v_lshl_add_u64 v[204:205], v[204:205], 0, v[206:207]
	global_store_dword v[204:205], v229, off sc1
	v_lshl_add_u64 v[204:205], v[204:205], 0, v[206:207]
	global_store_dword v[204:205], v230, off sc1
	v_lshl_add_u64 v[204:205], v[204:205], 0, v[206:207]
	global_store_dword v[204:205], v231, off sc1
	v_lshl_add_u64 v[204:205], v[204:205], 0, v[208:209]
	global_store_dword v[204:205], v232, off sc1
	v_lshl_add_u64 v[204:205], v[204:205], 0, v[206:207]
	global_store_dword v[204:205], v233, off sc1
	v_lshl_add_u64 v[204:205], v[204:205], 0, v[206:207]
	global_store_dword v[204:205], v234, off sc1
	v_lshl_add_u64 v[204:205], v[204:205], 0, v[206:207]
	global_store_dword v[204:205], v235, off sc1
	s_or_b64 exec, exec, s[0:1]
	s_lshl_b32 s0, s46, 6
	s_ashr_i32 s1, s0, 31
	s_waitcnt vmcnt(0)
	s_lshl_b64 s[0:1], s[0:1], 2
	s_add_u32 s0, s34, s0
	s_addc_u32 s1, s35, s1
	s_and_saveexec_b64 s[22:23], s[6:7]
	s_cbranch_execz .LBB0_692
	s_mov_b64 s[24:25], exec
	v_mbcnt_lo_u32_b32 v240, s24, 0
	v_mbcnt_hi_u32_b32 v240, s25, v240
	v_cmp_eq_u32_e32 vcc, 0, v240
	s_and_b64 s[26:27], exec, vcc
	s_mov_b64 exec, s[26:27]
	s_cbranch_execz .LBB0_692
	s_bcnt1_i32_b64 s4, s[24:25]
	v_mov_b32_e32 v240, s4
	global_atomic_add v129, v240, s[0:1]

.LBB0_694:
	global_load_dword v240, v129, s[0:1] sc1
	s_mov_b64 s[22:23], -1
	s_waitcnt vmcnt(0)
	v_readfirstlane_b32 s4, v240
	s_cmpk_gt_u32 s4, 0x7f
	s_cbranch_scc1 .LBB0_693
	s_add_i32 s24, s24, -1
	s_cmp_eq_u32 s24, 0
	s_cselect_b64 s[22:23], -1, 0
	s_sleep 2
	s_branch .LBB0_693
